# Grid-barrier census loads (16 per-XCC counters, and the 8-counter placement check) issued together instead of one round trip each
# speedup vs baseline: 1.0198x; 1.0066x over previous
; __device__ __forceinline__ unsigned xb_ld(unsigned* p)              { return __hip_atomic_load(p, __ATOMIC_RELAXED, __HIP_MEMORY_SCOPE_AGENT); }
; __global__ void __launch_bounds__(NWAVES * 64, 2) fwd_megakernel(Args args) {
;     ...
;     {
;         unsigned* bar = (unsigned*)(ws + WS_CTL) + CW_BAR;
;         bool ok = (G % 8) == 0;
;         for (int j = 0; j < 8; ++j) ok = ok && (xb_ld(&bar[XB_XCNT(j)]) == (unsigned)(G / 8));
;         const int rank = __builtin_amdgcn_readfirstlane((int)bst[10]);
;         if (ok && xbar.x < 8u && rank < G / 8) bid = (int)xbar.x + 8 * rank;
;     }
.LBB0_43:
	s_or_b64 exec, exec, s[0:1]
	s_ashr_i32 s6, s42, 31
	s_lshr_b32 s1, s6, 29
	s_add_i32 s1, s42, s1
	s_and_b32 s0, s42, 7
	s_ashr_i32 s7, s1, 3
	s_mov_b32 s24, 0
	s_cmp_eq_u32 s0, 0
	s_mov_b64 s[0:1], 0
	s_barrier
	s_cbranch_scc0 .LBB0_52
	v_mov_b32_e32 v0, 0x4000
	global_load_dword v1, v0, s[40:41] offset:1024 sc1
	global_load_dword v2, v0, s[40:41] offset:1280 sc1
	global_load_dword v3, v0, s[40:41] offset:1536 sc1
	global_load_dword v4, v0, s[40:41] offset:1792 sc1
	global_load_dword v5, v0, s[40:41] offset:2048 sc1
	global_load_dword v6, v0, s[40:41] offset:2304 sc1
	global_load_dword v7, v0, s[40:41] offset:2560 sc1
	global_load_dword v8, v0, s[40:41] offset:2816 sc1
	s_waitcnt vmcnt(0)
	v_cmp_ne_u32_e32 vcc, s7, v1
	s_cbranch_vccnz .LBB0_52
	v_cmp_ne_u32_e32 vcc, s7, v2
	s_cbranch_vccnz .LBB0_52
	v_cmp_ne_u32_e32 vcc, s7, v3
	s_cbranch_vccnz .LBB0_52
	v_cmp_ne_u32_e32 vcc, s7, v4
	s_cbranch_vccnz .LBB0_52
	v_cmp_ne_u32_e32 vcc, s7, v5
	s_cbranch_vccnz .LBB0_52
	v_cmp_ne_u32_e32 vcc, s7, v6
	s_cbranch_vccnz .LBB0_52
	v_cmp_ne_u32_e32 vcc, s7, v7
	s_cbranch_vccnz .LBB0_52
	v_readfirstlane_b32 s0, v8
	s_cmp_eq_u32 s0, s7
	s_cselect_b64 s[0:1], -1, 0

; __device__ __forceinline__ unsigned xb_ld(unsigned* p)              { return __hip_atomic_load(p, __ATOMIC_RELAXED, __HIP_MEMORY_SCOPE_AGENT); }
; __device__ __forceinline__ void xcd_barrier_complete(unsigned* bar, unsigned x, unsigned& nloc, unsigned& nx) {
;     const unsigned G = gridDim.x * gridDim.y * gridDim.z;
;     unsigned sum, cnt, mine, sp = 0u;
;     for (;;) {
;         sum = 0u; cnt = 0u; mine = 0u;
; #pragma unroll
;         for (unsigned j = 0; j < 16; ++j) { const unsigned c = xb_ld(&bar[XB_XCNT(j)]); sum += c; cnt += (c > 0u) ? 1u : 0u; mine = (j == x) ? c : mine; }
;         if (sum == G) break;
;         __builtin_amdgcn_s_sleep(1);
;         if ((++sp & 255u) == 0u) { if (xb_ld(&bar[XB_TMO])) break; if (sp > XB_SPIN_CAP) { atomicAdd(&bar[XB_TMO], 1u); break; } }
;     }
.LBB0_158:
	v_readlane_b32 s38, v252, 20
	v_readlane_b32 s39, v252, 21
	v_readlane_b32 s40, v254, 10
	s_waitcnt lgkmcnt(0)
	s_nop 3
	global_load_dword v0, v1, s[38:39] sc1
	global_load_dword v2, v1, s[38:39] offset:256 sc1
	global_load_dword v3, v1, s[38:39] offset:512 sc1
	global_load_dword v4, v1, s[38:39] offset:768 sc1
	global_load_dword v5, v1, s[38:39] offset:1024 sc1
	global_load_dword v6, v1, s[38:39] offset:1280 sc1
	global_load_dword v7, v1, s[38:39] offset:1536 sc1
	global_load_dword v8, v1, s[38:39] offset:1792 sc1
	global_load_dword v9, v1, s[38:39] offset:2048 sc1
	global_load_dword v10, v1, s[38:39] offset:2304 sc1
	global_load_dword v11, v1, s[38:39] offset:2560 sc1
	global_load_dword v12, v1, s[38:39] offset:2816 sc1
	global_load_dword v13, v1, s[38:39] offset:3072 sc1
	global_load_dword v14, v1, s[38:39] offset:3328 sc1
	global_load_dword v15, v1, s[38:39] offset:3584 sc1
	global_load_dword v16, v1, s[38:39] offset:3840 sc1
	s_waitcnt vmcnt(0)
	v_add_u32_e32 v17, v2, v0
	v_add_u32_e32 v17, v17, v3
	v_add_u32_e32 v17, v17, v4
	v_add_u32_e32 v17, v17, v5
	v_add_u32_e32 v17, v17, v6
	v_add_u32_e32 v17, v17, v7
	v_add_u32_e32 v17, v17, v8
	v_add_u32_e32 v17, v17, v9
	v_add_u32_e32 v17, v17, v10
	v_add_u32_e32 v17, v17, v11
	v_add_u32_e32 v17, v17, v12
	v_add_u32_e32 v17, v17, v13
	v_add_u32_e32 v17, v17, v14
	v_add_u32_e32 v17, v17, v15
	v_add_u32_e32 v17, v17, v16
	s_mov_b64 s[38:39], -1
	v_cmp_eq_u32_e32 vcc, s40, v17
	s_mov_b64 s[40:41], -1
	s_cbranch_vccnz .LBB0_157
	s_and_b32 s38, s44, 0xff
	s_cmp_eq_u32 s38, 0
	s_mov_b64 s[38:39], -1
	s_mov_b64 s[42:43], -1
	s_sleep 1
	s_cbranch_scc0 .LBB0_162
	v_readlane_b32 s38, v252, 18
	v_readlane_b32 s39, v252, 19
	s_nop 4
	global_load_dword v17, v1, s[38:39] sc1
	s_waitcnt vmcnt(0)
	v_cmp_eq_u32_e32 vcc, 0, v17
	s_cbranch_vccnz .LBB0_164
	s_mov_b64 s[42:43], 0
	s_mov_b64 s[38:39], -1
